# layer-1 weight copies moved out of the in-proj(0) tail (where their 26 MB run beside the last GEMM round) into P0
# speedup vs baseline: 1.0057x; 1.0057x over previous
; #define LAS __attribute__((address_space(3)))
; __global__ void __launch_bounds__(512, 2) fwd_megakernel(Args a) {
;     extern __shared__ __attribute__((aligned(16))) unsigned char lds_raw[];
;     LAS unsigned char* lds = (LAS unsigned char*)lds_raw;
;     cg::grid_group grid = cg::this_grid();
;     const int bid = blockIdx.x, G = gridDim.x;
;     if (threadIdx.x < 64) ((LAS unsigned*)(lds + 131072))[threadIdx.x] = 0u;
;     __syncthreads();
;     (void)xcd_barrier_post((unsigned*)(a.ws + WS_BAR), (volatile LAS unsigned*)(lds + 131072) + 8);
_Z14fwd_megakernel4Args:
	s_load_dwordx4 s[76:79], s[0:1], 0x80
	s_load_dwordx2 s[42:43], s[0:1], 0x90
	s_add_u32 s6, s0, 0x90
	v_and_b32_e32 v208, 0x3ff, v0
	s_mov_b32 s71, s2
	s_addc_u32 s7, s1, 0
	v_cmp_gt_u32_e32 vcc, 64, v208
	s_and_saveexec_b64 s[4:5], vcc
	v_lshl_add_u32 v1, v208, 2, 0
	v_add_u32_e32 v1, 0x20000, v1
	v_mov_b32_e32 v2, 0
	ds_write_b32 v1, v2
	s_or_b64 exec, exec, s[4:5]
	s_load_dword s2, s[0:1], 0x98
	s_waitcnt lgkmcnt(0)
	s_mov_b32 s4, 0
	s_nop 0
	v_writelane_b32 v255, s4, 40
	s_add_u32 s4, s78, 0x1700000
	s_addc_u32 s5, s79, 0
	v_writelane_b32 v253, s4, 0
	s_barrier
	s_nop 0
	v_writelane_b32 v253, s5, 1
	s_getreg_b32 s3, hwreg(HW_REG_XCC_ID, 0, 4)
	v_cmp_eq_u32_e64 s[8:9], 0, v208
	s_mov_b64 s[4:5], exec
	s_nop 0
	v_writelane_b32 v253, s8, 2
	s_nop 1
	v_writelane_b32 v253, s9, 3
	s_and_b64 s[8:9], s[4:5], s[8:9]
	s_mov_b64 exec, s[8:9]
	s_cbranch_execz .LBB0_5
	s_mov_b64 s[8:9], exec
	v_mbcnt_lo_u32_b32 v1, s8, 0
	v_mbcnt_hi_u32_b32 v1, s9, v1
	v_cmp_eq_u32_e32 vcc, 0, v1
	s_and_b64 s[10:11], exec, vcc
	s_mov_b64 exec, s[10:11]
	s_cbranch_execz .LBB0_5
	s_lshl_b32 s3, s3, 8
	s_bcnt1_i32_b64 s8, s[8:9]
	s_and_b32 s3, s3, 0xf00
	v_mov_b32_e32 v2, s8
	v_readlane_b32 s8, v253, 0
	v_mov_b32_e32 v1, s3
	v_readlane_b32 s9, v253, 1
	s_nop 4
	global_atomic_add v1, v2, s[8:9] offset:1024

; #define LAS __attribute__((address_space(3)))
; template <bool REMAP>
; __device__ __forceinline__ void p0_transpose_item(const float* W, int K, int N, bf16_t* WT, LAS float* scr, int item, int lane) {
;     const int nblk = N / 32, kb = item / nblk, nb = item % nblk, k0 = 64 * kb, n0 = 32 * nb;
;     const int r0 = REMAP ? win_row_of_col(n0) : n0;
; #pragma unroll
;     for (int i = 0; i < 32; ++i) { const int kk = 2 * i + (lane >> 5); scr[kk * 33 + (lane & 31)] = __builtin_nontemporal_load(W + (size_t)(k0 + kk) * N + n0 + (lane & 31)); }
; __device__ __forceinline__ void transposes_layer(const Args& a, int l, LAS unsigned char* lds, int lane, int wave, int vrot, int nvb) {
;     LAS float* scr = (LAS float*)(lds + wave * 16384);
;     constexpr int I_IN = (D / 64) * (PO / 32), I_OUT = (D / 64) * (D / 32);
;     bf16_t* WinT = (bf16_t*)(a.ws + WS_WIN) + (size_t)l * PO * D; bf16_t* WoutT = (bf16_t*)(a.ws + WS_WOUT) + (size_t)l * D * D;
;     for (int it = vrot * 8 + wave; it < I_IN + I_OUT; it += nvb * 8) {
;         if (it < I_IN) p0_transpose_item<true>(a.in[10] + (size_t)l * D * PO, D, PO, WinT, scr, it, lane);
;         else p0_transpose_item<false>(a.in[15] + (size_t)l * D * D, D, D, WoutT, scr, it - I_IN, lane);
;     }
.LBB0_38:
	v_writelane_b32 v255, s12, 41
	v_writelane_b32 v255, s13, 42
	v_writelane_b32 v255, s16, 43
	v_writelane_b32 v255, s17, 44
	v_writelane_b32 v255, s19, 45
	v_writelane_b32 v255, s21, 46
	v_writelane_b32 v255, s27, 47
	s_or_b64 exec, exec, s[12:13]
	s_ashr_i32 s3, s22, 6
	s_min_i32 s0, s42, 0xc0
	s_cmp_lt_i32 s71, s0
	s_cselect_b32 s1, s42, 0
	s_sub_i32 s0, s71, s0
	s_add_i32 s0, s0, s1
	s_lshl_b32 s0, s0, 3
	s_add_i32 s14, s3, s0
	s_cmpk_gt_i32 s14, 0x87f
	s_mov_b32 s1, 0
	s_cbranch_scc1 .LBB0_60
	v_lshlrev_b32_e32 v0, 2, v114
	v_bfe_u32 v12, v114, 5, 1
	v_and_b32_e32 v8, 0x7c, v0
	s_movk_i32 s4, 0x84
	v_mov_b32_e32 v0, 0x630
	v_mad_u32_u24 v50, v12, s4, v0
	v_mov_b32_e32 v0, 0xc60
	v_mad_u32_u24 v51, v12, s4, v0
	v_lshlrev_b32_e32 v0, 3, v114
	s_lshl_b32 s0, s3, 14
	v_and_b32_e32 v0, 56, v0
	s_add_i32 s0, s0, 0
	v_bfe_u32 v44, v114, 3, 3
	v_mul_u32_u24_e32 v6, 0x84, v0
	v_lshlrev_b32_e32 v0, 1, v0
	v_mov_b32_e32 v1, 0
	v_add_u32_e32 v10, s0, v8
	v_mul_u32_u24_e32 v11, 0x84, v12
	v_lshl_add_u64 v[2:3], s[78:79], 0, v[0:1]
	v_lshlrev_b32_e32 v0, 2, v44
	v_readlane_b32 s52, v253, 20
	s_mov_b64 s[4:5], 0xe00000
	v_add3_u32 v45, s0, v6, v0
	v_mov_b32_e32 v9, v1
	v_readlane_b32 s56, v253, 24
	v_readlane_b32 s57, v253, 25
	v_readlane_b32 s66, v253, 34
	v_readlane_b32 s67, v253, 35
	v_readlane_b32 s28, v255, 40
	s_nop 3
	s_mul_i32 s29, s28, 0xd00000
	s_add_u32 s56, s56, s29
	s_addc_u32 s57, s57, 0
	s_lshl_b32 s29, s28, 22
	s_add_u32 s66, s66, s29
	s_addc_u32 s67, s67, 0
	s_mul_i32 s30, s28, 0x680000
	s_mov_b32 s31, 0
	v_lshl_add_u64 v[2:3], v[2:3], 0, s[30:31]
	s_mul_i32 s29, s28, 0x480000
	s_sub_i32 s4, s4, s29
	s_lshl_b32 s0, s14, 1
	v_add_u32_e32 v49, v10, v11
	v_add_u32_e32 v50, v10, v50
	v_add_u32_e32 v51, v10, v51
	v_or_b32_e32 v13, 2, v12
	v_or_b32_e32 v14, 4, v12
	v_or_b32_e32 v15, 6, v12
	v_or_b32_e32 v16, 8, v12
	v_or_b32_e32 v17, 10, v12
	v_or_b32_e32 v18, 12, v12
	v_or_b32_e32 v19, 14, v12
	v_or_b32_e32 v20, 16, v12
	v_or_b32_e32 v21, 18, v12
	v_or_b32_e32 v22, 20, v12
	v_or_b32_e32 v23, 22, v12
	v_or_b32_e32 v24, 24, v12
	v_or_b32_e32 v25, 26, v12
	v_or_b32_e32 v26, 28, v12
	v_or_b32_e32 v27, 30, v12
	v_or_b32_e32 v28, 32, v12
	v_or_b32_e32 v29, 34, v12
	v_or_b32_e32 v30, 36, v12
	v_or_b32_e32 v31, 38, v12
	v_or_b32_e32 v32, 40, v12
	v_or_b32_e32 v33, 42, v12
	v_or_b32_e32 v34, 44, v12
	v_or_b32_e32 v35, 46, v12
	v_or_b32_e32 v36, 48, v12
	v_or_b32_e32 v37, 50, v12
	v_or_b32_e32 v38, 52, v12
	v_or_b32_e32 v39, 54, v12
	v_or_b32_e32 v40, 56, v12
	v_or_b32_e32 v41, 58, v12
	v_or_b32_e32 v42, 60, v12
	v_or_b32_e32 v43, 62, v12
	v_lshl_add_u64 v[4:5], v[2:3], 0, s[4:5]
	v_or_b32_e32 v46, 8, v44
	v_or_b32_e32 v47, 16, v44
	v_or_b32_e32 v48, 24, v44
	s_lshl_b32 s15, s42, 3
	v_lshl_add_u64 v[6:7], s[66:67], 0, v[8:9]
	v_lshl_add_u64 v[8:9], s[56:57], 0, v[8:9]
	s_lshl_b32 s16, s14, 5
	s_lshl_b32 s17, s42, 8
	s_add_i32 s18, s0, 0xfffff300
	s_lshl_b32 s19, s42, 4
	s_movk_i32 s20, 0x7fff
	s_mov_b32 s21, 0xffff0000
	s_movk_i32 s24, 0x3400
	v_add_u32_e32 v52, 0x400, v49
	v_add_u32_e32 v53, 0x400, v50
	v_add_u32_e32 v54, 0x400, v51
	v_add_u32_e32 v55, 0x800, v51
	v_add_u32_e32 v56, 0xc00, v51
	v_add_u32_e32 v57, 0x1000, v51
	v_readlane_b32 s53, v253, 21
	v_readlane_b32 s54, v253, 22
	v_readlane_b32 s55, v253, 23
	v_readlane_b32 s58, v253, 26
	v_readlane_b32 s59, v253, 27
	v_readlane_b32 s60, v253, 28
	v_readlane_b32 s61, v253, 29
	v_readlane_b32 s62, v253, 30
	v_readlane_b32 s63, v253, 31
	v_readlane_b32 s64, v253, 32
	v_readlane_b32 s65, v253, 33
	s_branch .LBB0_42

; __device__ __forceinline__ void p0_phase(const Args& a, LAS unsigned char* lds, int tid, int lane, int wave, int bid, int G) {
;     ...
;     {
;         const int nmod = G < 192 ? G : 192;
;         const int vrot = (bid >= nmod) ? bid - nmod : bid + (G - nmod);
;         transposes_layer(a, 0, lds, lane, wave, vrot, G);
;     }
.LBB0_60:
	s_cmpk_lg_i32 s42, 0x100
	s_cbranch_scc1 .Ltr_done
	v_readlane_b32 s0, v255, 40
	s_nop 3
	s_xor_b32 s0, s0, 1
	s_nop 0
	v_writelane_b32 v255, s0, 40
	s_cmp_lg_u32 s0, 1
	s_cbranch_scc1 .Ltr_done
	v_readlane_b32 s12, v255, 41
	v_readlane_b32 s13, v255, 42
	v_readlane_b32 s16, v255, 43
	v_readlane_b32 s17, v255, 44
	v_readlane_b32 s19, v255, 45
	v_readlane_b32 s21, v255, 46
	v_readlane_b32 s27, v255, 47
	s_nop 3
	s_branch .LBB0_38

; #define FRESH_TID() int tid = threadIdx.x; asm volatile("" : "+v"(tid)); const int lane = tid & 63, wave = __builtin_amdgcn_readfirstlane(tid >> 6)
;     __host__ __device__ bool next(int i, Unit& u) const {
;         const long L = (long)i * G + c; if (L >= nwg) return false;
;         int wgid = (int)L; { const int q = nwg / NXCD, r = nwg % NXCD, xcd = wgid % NXCD, off = wgid / NXCD; wgid = (xcd < r ? xcd * (q + 1) : r * (q + 1) + (xcd - r) * q) + off; }
;         const int nig = WGM * nN, gid = wgid / nig, fm = gid * WGM, gsz = (nM - fm) < WGM ? (nM - fm) : WGM;
;         u.pm = fm + ((wgid % nig) % gsz); u.pn = (wgid % nig) / gsz; return true;
; __global__ void __launch_bounds__(512, 2) fwd_megakernel(Args a) {
;     ...
;         {
;             pg8::Gemm g{(const bf16_t*)(a.ws + WS_H), (const bf16_t*)(a.ws + WS_WIN) + (size_t)l * PO * D, M, PO, D}; pg8::StaticOrder S; S.init(M, PO, G, bid);
;             pg8::EpiProj E{(bf16_t*)(a.ws + WS_PROJ)};
;             pg8::gemm_phase<pg8::EpiProj, pg8::StaticOrder, true, true>(lds, g, S, E);
;     ...
;             pg8::gemm_phase<pg8::EpiProj, pg8::StaticOrder, true, true>(lds, g, S, E);
;     ...
;             constexpr int N_UNITS = (M / 256) * (PO / 256), N_FULL = N_UNITS % 256;
;             if (l == 0) { if (G == 256 && bid >= N_FULL) { FRESH_TID(); (void)tid; transposes_layer(a, 1, lds, lane, wave, bid - N_FULL, 256 - N_FULL); }
;                           else if (G != 256) { FRESH_TID(); (void)tid; transposes_layer(a, 1, lds, lane, wave, bid, G); } }
.LBB0_187:
	s_or_b64 exec, exec, s[0:1]
	s_lshl_b32 s24, s71, 3
	s_lshl_b32 s44, s42, 3
	s_add_u32 s0, s78, 0x1200000
	v_writelane_b32 v253, s0, 36
	s_addc_u32 s0, s79, 0
	s_add_u32 s46, s78, 0x1800000
	s_addc_u32 s47, s79, 0
	s_add_u32 s72, s78, 0x1700200
	s_addc_u32 s73, s79, 0
	s_add_u32 s80, s78, 0x1700400
	s_addc_u32 s81, s79, 0
	s_add_u32 s82, s78, 0x1700500
	s_addc_u32 s83, s79, 0
	s_add_u32 s92, s78, 0x1700600
	s_addc_u32 s93, s79, 0
	s_add_u32 s94, s78, 0x1700700
	s_addc_u32 s95, s79, 0
	s_add_u32 s98, s78, 0x1700800
	s_addc_u32 s99, s79, 0
	s_add_u32 s54, s78, 0x1700900
	s_addc_u32 s55, s79, 0
	s_add_u32 s56, s78, 0x1700a00
	s_addc_u32 s57, s79, 0
	s_add_u32 s60, s78, 0x1700b00
	s_addc_u32 s61, s79, 0
	s_add_u32 s62, s78, 0x1700c00
	s_addc_u32 s63, s79, 0
	v_writelane_b32 v253, s0, 37
	s_add_u32 s0, s78, 0x1700d00
	s_addc_u32 s1, s79, 0
	v_writelane_b32 v253, s0, 38
	v_mov_b32_e32 v173, 0
	v_writelane_b32 v255, s60, 0
	v_writelane_b32 v253, s1, 39
	s_add_u32 s0, s78, 0x1700e00
	s_addc_u32 s1, s79, 0
	v_writelane_b32 v253, s0, 40
	v_writelane_b32 v255, s61, 1
	v_writelane_b32 v255, s62, 2
	v_writelane_b32 v253, s1, 41
	s_add_u32 s0, s78, 0x1700f00
	s_addc_u32 s1, s79, 0
	v_writelane_b32 v253, s0, 42
	v_writelane_b32 v255, s63, 3
	s_mov_b32 s87, 0
	v_writelane_b32 v253, s1, 43
	s_add_u32 s0, s78, 0x1701000
	s_addc_u32 s1, s79, 0
	v_writelane_b32 v253, s0, 44
	v_mov_b32_e32 v209, 0x358637bd
	v_mov_b32_e32 v252, 0x1000
	v_writelane_b32 v253, s1, 45
	s_add_u32 s0, s78, 0x1701100
	s_addc_u32 s1, s79, 0
	v_writelane_b32 v253, s0, 46
	v_mov_b32_e32 v221, 0x2000
	v_mov_b32_e32 v212, 1
	v_writelane_b32 v253, s1, 47
	s_add_u32 s0, s78, 0x1701200
	s_addc_u32 s1, s79, 0
	v_writelane_b32 v253, s0, 48
	v_mov_b64_e32 v[174:175], 0x374
	v_mov_b64_e32 v[176:177], 0x373
	v_writelane_b32 v253, s1, 49
	s_add_u32 s0, s78, 0x1701300
	s_addc_u32 s1, s79, 0
	v_writelane_b32 v253, s0, 50
	v_mov_b32_e32 v222, 0xc60
	v_mov_b32_e32 v223, 0xf149f2ca
	v_writelane_b32 v253, s1, 51
	s_add_u32 s0, s78, 0x1703400
	s_addc_u32 s1, s79, 0
	v_writelane_b32 v253, s0, 52
	v_mov_b32_e32 v224, 0x800
	v_mov_b32_e32 v225, 0xfffffc00
	v_writelane_b32 v253, s1, 53
	s_add_u32 s0, s78, 0x1703500
	s_addc_u32 s1, s79, 0
	s_add_u32 s74, s78, 0x3a00000
	s_addc_u32 s75, s79, 0
	v_writelane_b32 v253, s0, 54
	s_cmpk_lt_i32 s71, 0x374
	v_mov_b32_e32 v226, 0x3c00
	v_writelane_b32 v253, s1, 55
	s_cselect_b64 s[0:1], -1, 0
	v_writelane_b32 v253, s0, 56
	s_ashr_i32 s33, s71, 31
	s_ashr_i32 s91, s42, 31
	v_writelane_b32 v253, s1, 57
	s_lshr_b32 s0, s33, 29
	s_add_i32 s0, s71, s0
	s_ashr_i32 s3, s0, 3
	s_and_b32 s0, s0, -8
	s_sub_i32 s4, s71, s0
	s_mul_i32 s0, s4, 0x6e
	s_add_i32 s5, s0, 4
	s_cmpk_lg_i32 s42, 0x100
	s_cselect_b64 s[6:7], -1, 0
	s_cmpk_lt_i32 s71, 0x74
	s_cselect_b64 s[0:1], -1, 0
	v_writelane_b32 v253, s6, 58
	s_mov_b64 s[0:1], -1
	v_writelane_b32 v255, s33, 4
	v_writelane_b32 v253, s7, 59
	v_writelane_b32 v253, s0, 60
	v_mov_b32_e32 v232, v173
	v_mov_b32_e32 v233, v173
	v_writelane_b32 v253, s1, 61
	s_add_u32 s0, s78, 0x1000000
	s_addc_u32 s1, s79, 0
	v_writelane_b32 v253, s0, 62
	v_mov_b32_e32 v234, v173
	v_mov_b32_e32 v235, v173
	v_writelane_b32 v253, s1, 63
	s_add_u32 s0, s78, 0x680000
	v_readlane_b32 s8, v253, 20
	v_readlane_b32 s9, v253, 21
	v_readlane_b32 s10, v253, 22
	v_readlane_b32 s11, v253, 23
	v_readlane_b32 s12, v253, 24
	v_readlane_b32 s13, v253, 25
	v_readlane_b32 s14, v253, 26
	v_readlane_b32 s15, v253, 27
	v_readlane_b32 s16, v253, 28
	v_readlane_b32 s17, v253, 29
	v_readlane_b32 s18, v253, 30
	v_readlane_b32 s19, v253, 31
	s_addc_u32 s1, s79, 0
	v_readlane_b32 s20, v253, 32
	v_readlane_b32 s21, v253, 33
	v_readlane_b32 s22, v253, 34
	v_readlane_b32 s23, v253, 35
	s_mov_b64 s[8:9], s[12:13]
	v_writelane_b32 v254, s0, 0
	s_mov_b64 s[10:11], s[14:15]
	s_mov_b64 s[12:13], s[16:17]
	s_mov_b64 s[14:15], s[18:19]
	s_mov_b64 s[16:17], s[20:21]
	s_mov_b64 s[18:19], s[22:23]
	v_writelane_b32 v254, s1, 1
	s_add_u32 s0, s18, 0x400000
	s_addc_u32 s1, s19, 0
	v_writelane_b32 v254, s0, 2
	v_mov_b64_e32 v[178:179], 0x100
	v_mov_b64_e32 v[180:181], 0xff
	v_writelane_b32 v254, s1, 3
	s_add_u32 s0, s8, 0xd00000
	s_addc_u32 s1, s9, 0
	v_writelane_b32 v254, s0, 4
	s_mov_b32 s96, 0x800000
	s_movk_i32 s97, 0x1200
	v_writelane_b32 v254, s1, 5
	v_writelane_b32 v254, s24, 6
	s_add_i32 s0, s24, 0xfffffc60
	v_writelane_b32 v254, s0, 7
	s_add_u32 s0, s78, 0x1703800
	v_writelane_b32 v254, s0, 8
	s_addc_u32 s0, s79, 0
	s_bitcmp0_b32 s71, 3
	v_writelane_b32 v254, s0, 9
	s_cselect_b64 s[0:1], -1, 0
	v_writelane_b32 v254, s0, 10
	s_cmpk_lt_i32 s71, 0x100
	s_movk_i32 s84, 0x90
	v_writelane_b32 v254, s1, 11
	s_cselect_b64 s[0:1], -1, 0
	s_add_u32 s50, s76, 0x4408000
	s_addc_u32 s51, s77, 0
	s_add_u32 s40, s76, 0x4488000
	v_writelane_b32 v254, s0, 12
	s_addc_u32 s41, s77, 0
	s_mov_b64 s[26:27], 0x1000
	v_writelane_b32 v254, s1, 13
	s_add_u32 s0, s76, 0x4508000
	v_writelane_b32 v254, s0, 14
	s_addc_u32 s0, s77, 0
	v_writelane_b32 v254, s0, 15
	s_add_u32 s0, s76, 0x4400000
	v_writelane_b32 v254, s0, 16
	s_addc_u32 s0, s77, 0
	v_writelane_b32 v254, s0, 17
	s_add_u32 s0, s76, 0x4608000
	v_writelane_b32 v254, s0, 18
	s_addc_u32 s0, s77, 0
	v_writelane_b32 v254, s0, 19
	s_add_u32 s0, s76, 0x5608000
	v_writelane_b32 v254, s0, 20
	s_addc_u32 s0, s77, 0
	v_writelane_b32 v254, s0, 21
	s_add_u32 s0, s78, 0xe00000
	v_writelane_b32 v254, s0, 22
	s_addc_u32 s0, s79, 0
	s_add_u32 s58, s78, 0xaa00000
	v_writelane_b32 v254, s0, 23
	s_addc_u32 s59, s79, 0
	s_bfe_u32 s85, s71, 0x10003
	s_lshl_b32 s0, s4, 5
	s_add_u32 s6, s76, 0x4000000
	s_addc_u32 s7, s77, 0
	v_writelane_b32 v254, s6, 24
	s_mul_i32 s1, s4, 0x6f
	v_writelane_b32 v255, s85, 5
	v_writelane_b32 v254, s7, 25
	s_add_u32 s6, s78, 0xca00000
	s_addc_u32 s7, s79, 0
	s_cmp_lt_i32 s4, 4
	s_cselect_b32 s1, s1, s5
	s_add_i32 s1, s1, s3
	v_writelane_b32 v254, s6, 26
	s_mul_hi_i32 s5, s1, 0x4ec4ec4f
	s_mov_b64 s[88:89], 0x80
	v_writelane_b32 v254, s7, 27
	s_lshr_b32 s6, s5, 31
	s_ashr_i32 s5, s5, 5
	s_add_i32 s5, s5, s6
	s_mul_i32 s6, s5, 0x68
	s_lshl_b32 s5, s5, 3
	s_sub_i32 s6, s1, s6
	s_sub_i32 s1, 0x44, s5
	s_min_u32 s7, s1, 8
	s_cmp_lt_i32 s4, 0
	s_mul_i32 s4, s4, 33
	s_cselect_b32 s0, s4, s0
	s_add_i32 s0, s0, s3
	s_ashr_i32 s1, s0, 31
	s_lshr_b32 s1, s1, 27
	s_add_i32 s1, s0, s1
	s_and_b32 s3, s1, 0xffe0
	s_sub_i32 s0, s0, s3
	s_bfe_i32 s3, s0, 0x80000
	s_bfe_u32 s3, s3, 0x3000c
	s_add_i32 s3, s0, s3
	s_and_b32 s4, s3, 0xf8
	s_sub_i32 s0, s0, s4
	s_ashr_i32 s1, s1, 5
	s_bfe_i32 s3, s3, 0x80000
	s_lshl_b32 s1, s1, 3
	s_sext_i32_i16 s3, s3
	s_sext_i32_i8 s0, s0
	s_add_i32 s8, s1, s0
	s_ashr_i32 s0, s3, 3
	v_writelane_b32 v254, s0, 28
	s_lshr_b32 s0, s3, 3
	s_bfe_i64 s[0:1], s[0:1], 0x100000
	s_lshl_b64 s[0:1], s[0:1], 19
	v_writelane_b32 v254, s0, 29
	v_cvt_f32_ubyte0_e32 v1, s7
	s_waitcnt lgkmcnt(0)
;     __host__ __device__ bool next(int i, Unit& u) const {
;         const long L = (long)i * G + c; if (L >= nwg) return false;
;         int wgid = (int)L; { const int q = nwg / NXCD, r = nwg % NXCD, xcd = wgid % NXCD, off = wgid / NXCD; wgid = (xcd < r ? xcd * (q + 1) : r * (q + 1) + (xcd - r) * q) + off; }
;         const int nig = WGM * nN, gid = wgid / nig, fm = gid * WGM, gsz = (nM - fm) < WGM ? (nM - fm) : WGM;
;         u.pm = fm + ((wgid % nig) % gsz); u.pn = (wgid % nig) / gsz; return true;
	v_cvt_f32_i32_e32 v0, s6
	v_writelane_b32 v254, s1, 30
	s_mov_b32 s0, s8
	v_rcp_iflag_f32_e32 v2, v1
	s_ashr_i32 s9, s8, 31
	v_writelane_b32 v254, s0, 31
	s_mov_b32 s90, 0x3e38aa3b
	v_mul_f32_e32 v2, v0, v2
	v_writelane_b32 v254, s1, 32
	s_lshl_b64 s[0:1], s[8:9], 19
	s_add_u32 s0, s46, s0
	s_addc_u32 s1, s47, s1
	s_add_u32 s8, s0, 0x40000
	v_writelane_b32 v254, s0, 33
	v_trunc_f32_e32 v2, v2
	s_addc_u32 s9, s1, 0
	v_writelane_b32 v254, s1, 34
	s_ashr_i32 s0, s6, 30
	v_fma_f32 v0, -v2, v1, v0
	s_or_b32 s3, s0, 1
	v_cmp_ge_f32_e64 s[0:1], |v0|, v1
	v_cvt_i32_f32_e32 v0, v2
	s_and_b64 s[0:1], s[0:1], exec
	v_writelane_b32 v254, s8, 35
	s_mul_i32 s0, s43, s42
	s_mul_i32 s0, s0, s2
	v_writelane_b32 v254, s9, 36
	v_writelane_b32 v254, s0, 37
	s_cselect_b32 s0, s3, 0
	v_readfirstlane_b32 s1, v0
	s_add_i32 s0, s1, s0
	s_mul_i32 s1, s0, s7
	s_sub_i32 s1, s6, s1
	s_sext_i32_i8 s1, s1
	s_add_i32 s1, s5, s1
	v_writelane_b32 v254, s1, 38
	s_sext_i32_i8 s0, s0
	v_writelane_b32 v254, s0, 39
	s_lshl_b32 s0, s71, 2
	v_writelane_b32 v254, s0, 40
	s_lshl_b32 s0, s42, 2
	v_writelane_b32 v254, s0, 41
	s_lshl_b32 s0, s71, 6
	v_writelane_b32 v254, s0, 42
	s_lshl_b32 s0, s42, 6
	v_writelane_b32 v254, s0, 43
	s_add_i32 s0, 0, 0x20020
	v_writelane_b32 v254, s0, 44
	s_add_i32 s0, 0, 0x20024
	v_writelane_b32 v254, s0, 45
	s_add_i32 s0, 0, 0x20080
	v_writelane_b32 v254, s0, 46
	s_add_i32 s0, 0, 0x4c80
	v_writelane_b32 v254, s0, 47
	v_writelane_b32 v254, s72, 48
	s_ashr_i32 s45, s44, 31
	v_mbcnt_lo_u32_b32 v0, -1, 0
	v_writelane_b32 v254, s73, 49
	v_writelane_b32 v254, s80, 50
	v_mbcnt_hi_u32_b32 v213, -1, v0
	s_lshl_b64 s[12:13], s[44:45], 11
	v_writelane_b32 v254, s81, 51
	v_writelane_b32 v254, s82, 52
	v_and_b32_e32 v0, 64, v213
	v_writelane_b32 v255, s12, 6
	v_writelane_b32 v254, s83, 53
	v_writelane_b32 v254, s92, 54
	v_add_u32_e32 v214, 64, v0
	v_xor_b32_e32 v215, 1, v213
	v_writelane_b32 v254, s93, 55
	v_writelane_b32 v254, s94, 56
	v_xor_b32_e32 v216, 2, v213
	v_xor_b32_e32 v217, 4, v213
	v_writelane_b32 v254, s95, 57
	v_writelane_b32 v254, s98, 58
	v_xor_b32_e32 v218, 8, v213
	v_xor_b32_e32 v219, 16, v213
	v_writelane_b32 v254, s99, 59
	v_writelane_b32 v254, s54, 60
	v_xor_b32_e32 v220, 32, v213
	s_lshl_b32 s43, s42, 4
	v_writelane_b32 v254, s55, 61
	v_writelane_b32 v254, s56, 62
	s_mov_b64 s[4:5], -1
	s_mov_b32 s66, s87
	v_writelane_b32 v254, s57, 63
	v_writelane_b32 v255, s13, 7
	s_barrier
	s_branch .LBB0_191
